# w_mo / w_up weight transposes moved out of phase 0 into the arrive-to-release window of the grid barriers after phases 1 and 2 (one 4-tile step per workgroup each)
# speedup vs baseline: 1.0189x; 1.0112x over previous
.LBB0_506:
	s_movk_i32 s32, 0x11c0
	v_readlane_b32 s0, v254, 62
	s_cmpk_lg_u32 s0, 0x100
	s_cbranch_scc1 .Ltp_bound
	s_movk_i32 s32, 0x880

.Lbar_wait:
	v_readlane_b32 s10, v254, 62
	s_cmpk_lg_u32 s10, 0x100
	s_cbranch_scc1 .Lbs_no0
	s_cmp_eq_u32 s70, 1
	s_cbranch_scc1 .Lbs_no0_y
	s_cmp_lg_u32 s70, 2
	s_cbranch_scc1 .Lbs_no0
.Lbs_no0_y:
	v_mov_b32_e32 v142, v5
	s_branch .Lbs_step

.Lbs_no1_y:
	s_branch .Lbs_step
.Lbs_no1:
	s_branch .LBB0_1383
.Lbs_step:
	s_mov_b64 exec, -1
	v_readlane_b32 s0, v255, 2
	s_cmp_eq_u32 s70, 1
	s_cbranch_scc0 .Lbs_p2
	s_add_i32 s0, s0, 0x880
	s_movk_i32 s32, 0xc80
	s_branch .Lbs_pd
.Lbs_p2:
	s_add_i32 s0, s0, 0xc80
	s_movk_i32 s32, 0xf00
.Lbs_pd:
	v_mov_b32_e32 v143, s0
	v_readlane_b32 s0, v254, 56
	v_readlane_b32 s1, v254, 57
	s_load_dwordx2 s[18:19], s[0:1], 0x108
	v_ashrrev_i32_e32 v1, 4, v174
	s_waitcnt vmcnt(0) lgkmcnt(0)
.Ltb_BB0_506:
	v_readlane_b32 s0, v143, 0
	s_cmp_ge_i32 s0, s32
	s_waitcnt lgkmcnt(0)
	s_barrier
	v_readlane_b32 s1, v255, 3
	s_cbranch_scc1 .Ltb_end
	s_add_u32 s6, s18, 0x1e80000
	s_addc_u32 s7, s19, 0
	s_add_u32 s8, s18, 0x1380000
	s_addc_u32 s9, s19, 0
	s_add_u32 s10, s18, 0x1bd3d800
	v_ashrrev_i32_e32 v27, 3, v174
	v_lshlrev_b32_e32 v2, 3, v174
	s_addc_u32 s11, s19, 0
	s_waitcnt vmcnt(0)
	v_and_b32_e32 v36, 56, v2
	v_lshlrev_b32_e32 v2, 2, v174
	s_add_u32 s12, s18, 0x780000
	v_lshlrev_b32_e32 v4, 1, v27
	v_lshrrev_b32_e32 v5, 2, v27
	v_readlane_b32 s0, v254, 62
	v_and_b32_e32 v2, 60, v2
	s_addc_u32 s13, s19, 0
	v_and_b32_e32 v4, 24, v4
	v_and_b32_e32 v5, 4, v5
	v_and_b32_e32 v6, 35, v27
	v_readlane_b32 s1, v254, 63
	s_mov_b32 s2, s0
	s_lshl_b32 s34, s0, 2
	s_movk_i32 s0, 0x104
	v_lshl_add_u32 v3, v2, 2, 0
	v_or3_b32 v37, v5, v6, v4
	v_mul_lo_u32 v4, v1, s0
	v_mad_u32_u24 v48, v36, s0, 0
	v_readlane_b32 s0, v143, 0
	s_lshl_b32 s33, s0, 6
	s_lshl_b32 s35, s2, 8
	s_lshl_b32 s36, s0, 2
	s_lshl_b32 s37, s2, 4
	s_lshl_b32 s38, s2, 1
	s_lshl_b32 s39, s2, 7
	s_mul_i32 s40, s2, 0xc0
	s_mul_i32 s41, s2, 12
	s_lshl_b32 s42, s2, 6
	s_waitcnt vmcnt(12)
	v_lshlrev_b32_e32 v38, 2, v2
	v_add_u32_e32 v49, v3, v4
	s_mov_b32 s43, s0
	v_readlane_b32 s1, v255, 3
	s_branch .Ltb_BB0_510

.Ltb_end:
	s_mov_b32 s32, 0
	s_mov_b64 exec, -1
	s_mov_b64 s[0:1], -1
	v_readlane_b32 s2, v254, 2
	v_readlane_b32 s3, v254, 3
	s_nop 1
	s_mov_b64 exec, s[2:3]
	s_cbranch_execz .LBB0_1383
	v_mov_b32_e32 v5, v142
	v_readlane_b32 s8, v254, 6
	v_readlane_b32 s9, v254, 7
	s_mov_b32 s24, 0
	s_nop 4
	s_branch .Lbar_spin
